# v49: LN1/LN2 rows assigned XCD-locally (rows 2048x.. to WGs with blockIdx%8==x) so PRE1/PRE2 reads hit the L2 that just wrote them (no invalidate at those barriers)
# speedup vs baseline: 1.0061x; 1.0061x over previous
; __device__ __forceinline__ f32x4 unpk4(u32x2 w) { f32x4 r; r.x = bflo(w.x); r.y = bfhi(w.x); r.z = bflo(w.y); r.w = bfhi(w.y); return r; }
; template <int WHICH, int NRW>
; __device__ __forceinline__ void ln_rows(const Params& p, const int row0, const int lane, const f32x4 (&gv)[4], const f32x4 (&bv)[4]) {
;   bf16_t* X1b = (bf16_t*)(p.ws + OFF_X1B);
;   f32x4 v[NRW][4];
; #pragma unroll
;   for (int h = 0; h < NRW; ++h) {
;     const int row = row0 + h;
;     if (row < MP) {
;       const bf16_t* xr = (const bf16_t*)(p.ws + (WHICH == 1 ? OFF_PRE1 : OFF_PRE2)) + (size_t)row * DM;
; #pragma unroll
;       for (int j = 0; j < 4; ++j) v[h][j] = unpk4(*(const u32x2*)(xr + j * 256 + lane * 4));
;     } else {
;       const float* SL = (const float*)(p.ws + (WHICH == 1 ? OFF_SLAB_WO : OFF_SLAB_DN)) + (size_t)(row - MP) * DM;
;       constexpr int NS = (WHICH == 1) ? 8 : 11;
; #pragma unroll
;       for (int j = 0; j < 4; ++j) {
;         f32x4 a;
;         if (WHICH == 1) a = *(const f32x4*)(p.in[1] + (size_t)(row - MP) * DM + j * 256 + lane * 4) * ALPHA_F;
;         else a = unpk4(*(const u32x2*)(X1b + (size_t)row * DM + j * 256 + lane * 4)) * ALPHA_F;
; #pragma unroll
;         for (int q = 0; q < NS; ++q) a += *(const f32x4*)(SL + (size_t)q * MS * DM + j * 256 + lane * 4);
;         v[h][j] = a;
;       }
;     }
;   }
;   float s[NRW], s2[NRW];
; #pragma unroll
;   for (int h = 0; h < NRW; ++h) { s[h] = 0.f;
; #pragma unroll
;     for (int j = 0; j < 4; ++j) s[h] += (v[h][j].x + v[h][j].y) + (v[h][j].z + v[h][j].w); }
; template <int WHICH>
; __device__ __forceinline__ void ln_phase(const Params& p) {
;   const int lane = threadIdx.x & 63, wid = threadIdx.x >> 6;
;   const int gw = blockIdx.x * NWAVE + wid, NGW = gridDim.x * NWAVE;
;   const float* gam = p.in[WHICH == 1 ? 20 : 26]; const float* bet = p.in[WHICH == 1 ? 21 : 27];
;   f32x4 gv[4], bv[4];
; #pragma unroll
;   for (int j = 0; j < 4; ++j) { gv[j] = *(const f32x4*)(gam + j * 256 + lane * 4); bv[j] = *(const f32x4*)(bet + j * 256 + lane * 4); }
;   for (int rp = gw; rp < MP / 2; rp += NGW) ln_rows<WHICH, 2>(p, rp * 2, lane, gv, bv);
.LBB0_889:
	s_or_b64 exec, exec, s[0:1]
	v_readlane_b32 s4, v244, 35
	v_and_b32_e32 v34, 0xfc, v1
	v_readlane_b32 s8, v244, 39
	v_readlane_b32 s9, v244, 40
	v_readlane_b32 s10, v244, 41
	v_readlane_b32 s11, v244, 42
	v_readlane_b32 s12, v244, 43
	v_readlane_b32 s13, v244, 44
	v_lshlrev_b32_e32 v188, 2, v34
	v_readlane_b32 s14, v244, 45
	v_readlane_b32 s15, v244, 46
	s_mov_b64 s[8:9], s[12:13]
	s_waitcnt lgkmcnt(0)
	s_barrier
	s_mov_b64 s[10:11], s[14:15]
	global_load_dwordx4 v[2:5], v188, s[8:9]
	global_load_dwordx4 v[6:9], v188, s[10:11]
	global_load_dwordx4 v[10:13], v188, s[8:9] offset:1024
	global_load_dwordx4 v[14:17], v188, s[10:11] offset:1024
	global_load_dwordx4 v[18:21], v188, s[8:9] offset:2048
	global_load_dwordx4 v[22:25], v188, s[10:11] offset:2048
	global_load_dwordx4 v[26:29], v188, s[8:9] offset:3072
	global_load_dwordx4 v[30:33], v188, s[10:11] offset:3072
	v_readlane_b32 s5, v244, 36
	s_movk_i32 s0, 0x2000
	v_mov_b32_e32 v191, 0
	v_cmp_gt_i32_e64 s[4:5], s0, v182
	v_lshlrev_b32_e32 v190, 1, v34
	v_lshl_add_u32 v192, v183, 1, s3
	v_readlane_b32 s6, v244, 37
	v_readlane_b32 s7, v244, 38
	v_readlane_b32 s16, v244, 47
	v_readlane_b32 s17, v244, 48
	v_readlane_b32 s18, v244, 49
	v_readlane_b32 s19, v244, 50
	s_and_saveexec_b64 s[0:1], s[4:5]
	s_cbranch_execz .LBB0_892
	v_mbcnt_hi_u32_b32 v34, -1, v185
	v_and_b32_e32 v35, 64, v34
	v_add_u32_e32 v35, 64, v35
	v_xor_b32_e32 v36, 1, v34
	v_cmp_lt_i32_e32 vcc, v36, v35
	v_lshl_add_u32 v38, v183, 1, s3
	s_lshl_b32 s3, s33, 4
	v_cndmask_b32_e32 v36, v34, v36, vcc
	v_lshlrev_b32_e32 v41, 2, v36
	v_xor_b32_e32 v36, 2, v34
	v_cmp_lt_i32_e32 vcc, v36, v35
	s_mov_b64 s[6:7], 0
	s_mov_b32 s8, 0x3a800000
	v_cndmask_b32_e32 v36, v34, v36, vcc
	v_lshlrev_b32_e32 v78, 2, v36
	v_xor_b32_e32 v36, 4, v34
	v_cmp_lt_i32_e32 vcc, v36, v35
	s_mov_b32 s9, 0x800000
	s_movk_i32 s10, 0x1fff
	v_cndmask_b32_e32 v36, v34, v36, vcc
	v_lshlrev_b32_e32 v79, 2, v36
	v_xor_b32_e32 v36, 8, v34
	v_cmp_lt_i32_e32 vcc, v36, v35
	v_mov_b32_e32 v40, 0x3727c5ac
	v_mov_b32_e32 v83, v182
	v_cndmask_b32_e32 v36, v34, v36, vcc
	v_lshlrev_b32_e32 v80, 2, v36
	v_xor_b32_e32 v36, 16, v34
	v_cmp_lt_i32_e32 vcc, v36, v35
	s_nop 1
	v_cndmask_b32_e32 v36, v34, v36, vcc
	v_lshlrev_b32_e32 v81, 2, v36
	v_xor_b32_e32 v36, 32, v34
	v_cmp_lt_i32_e32 vcc, v36, v35
	s_nop 1
	v_cndmask_b32_e32 v34, v34, v36, vcc
	v_lshlrev_b32_e32 v82, 2, v34
	v_lshl_add_u64 v[34:35], s[96:97], 0, v[190:191]
	v_lshl_add_u64 v[36:37], s[20:21], 0, v[190:191]
	s_cmp_lg_u32 s33, 0x100
	s_cbranch_scc1 .Lln1map_keep
	v_readlane_b32 s98, v244, 33
	s_nop 3
	s_and_b32 s99, s98, 7
	s_lshl_b32 s99, s99, 11
	s_lshr_b32 s98, s98, 3
	s_lshl_b32 s98, s98, 6
	s_add_u32 s98, s98, s99
	v_lshl_add_u32 v38, v183, 1, s98
	s_mov_b32 s3, 16
.Lln1map_keep:
.LBB0_891:
	v_ashrrev_i32_e32 v39, 31, v38
	v_lshlrev_b64 v[64:65], 11, v[38:39]
	v_lshl_add_u64 v[42:43], v[34:35], 0, v[64:65]
	global_load_dwordx2 v[44:45], v[42:43], off offset:1024
	global_load_dwordx2 v[46:47], v[42:43], off offset:1536
	global_load_dwordx2 v[48:49], v[42:43], off
	global_load_dwordx2 v[50:51], v[42:43], off offset:512
	v_add_u32_e32 v42, 1, v38
	v_ashrrev_i32_e32 v43, 31, v42
	v_lshlrev_b64 v[42:43], 11, v[42:43]
	v_lshl_add_u64 v[52:53], v[34:35], 0, v[42:43]
	global_load_dwordx2 v[54:55], v[52:53], off offset:1024
	global_load_dwordx2 v[70:71], v[52:53], off offset:1536
	global_load_dwordx2 v[72:73], v[52:53], off
	global_load_dwordx2 v[84:85], v[52:53], off offset:512
	v_lshl_add_u64 v[64:65], v[36:37], 0, v[64:65]
	v_lshl_add_u64 v[42:43], v[36:37], 0, v[42:43]
	v_add_u32_e32 v83, s66, v83
	v_add_u32_e32 v38, s3, v38
	s_waitcnt vmcnt(7)
	v_lshlrev_b32_e32 v66, 16, v44
	v_and_b32_e32 v67, 0xffff0000, v44
	s_waitcnt vmcnt(5)
	v_lshlrev_b32_e32 v77, 16, v49
	v_lshlrev_b32_e32 v76, 16, v48
	v_and_b32_e32 v87, 0xffff0000, v49
	v_and_b32_e32 v86, 0xffff0000, v48
	s_waitcnt vmcnt(4)
	v_lshlrev_b32_e32 v75, 16, v51
	v_lshlrev_b32_e32 v74, 16, v50
	v_and_b32_e32 v89, 0xffff0000, v51
	v_and_b32_e32 v88, 0xffff0000, v50
	v_pk_add_f32 v[90:91], v[76:77], v[86:87]
	v_pk_add_f32 v[92:93], v[74:75], v[88:89]
	v_lshlrev_b32_e32 v68, 16, v45
	v_and_b32_e32 v69, 0xffff0000, v45
	v_and_b32_e32 v59, 0xffff0000, v46
	v_add_f32_e32 v39, v90, v91
	v_pk_add_f32 v[90:91], v[92:93], v[92:93] op_sel:[0,1] op_sel_hi:[1,0]
	v_lshlrev_b32_e32 v63, 16, v46
	v_lshlrev_b32_e32 v61, 16, v47
	v_and_b32_e32 v57, 0xffff0000, v47
	s_waitcnt vmcnt(2)
	v_lshlrev_b32_e32 v51, 16, v70
	v_and_b32_e32 v47, 0xffff0000, v70
	v_lshlrev_b32_e32 v49, 16, v71
	v_and_b32_e32 v45, 0xffff0000, v71
	v_add_f32_e32 v60, v66, v67
	v_add_f32_e32 v56, v68, v69
	s_waitcnt vmcnt(1)
	v_lshlrev_b32_e32 v71, 16, v73
	v_lshlrev_b32_e32 v70, 16, v72
	v_and_b32_e32 v95, 0xffff0000, v73
	v_and_b32_e32 v94, 0xffff0000, v72
	v_add_f32_e32 v62, 0, v39
	v_mov_b32_e32 v91, v59
	v_pk_add_f32 v[92:93], v[60:61], v[56:57]
	v_pk_add_f32 v[96:97], v[70:71], v[94:95]
	v_pk_add_f32 v[90:91], v[62:63], v[90:91]
	s_waitcnt vmcnt(0)
	v_lshlrev_b32_e32 v73, 16, v85
	v_lshlrev_b32_e32 v72, 16, v84
	v_and_b32_e32 v85, 0xffff0000, v85
	v_and_b32_e32 v84, 0xffff0000, v84
	v_add_f32_e32 v39, v96, v97
	v_pk_add_f32 v[90:91], v[90:91], v[92:93]
	v_pk_add_f32 v[98:99], v[72:73], v[84:85]
	v_add_f32_e32 v50, 0, v39
	v_add_f32_e32 v39, v90, v91
	v_lshlrev_b32_e32 v52, 16, v54
	v_and_b32_e32 v53, 0xffff0000, v54
	v_lshlrev_b32_e32 v54, 16, v55
	v_and_b32_e32 v55, 0xffff0000, v55
	v_pk_add_f32 v[96:97], v[98:99], v[98:99] op_sel:[0,1] op_sel_hi:[1,0]
	ds_bpermute_b32 v46, v41, v39
	v_add_f32_e32 v48, v52, v53
	v_add_f32_e32 v44, v54, v55
	v_mov_b32_e32 v97, v47
	v_pk_add_f32 v[98:99], v[48:49], v[44:45]
	v_pk_add_f32 v[92:93], v[50:51], v[96:97]
	s_waitcnt lgkmcnt(0)
; template <int WHICH, int NRW>
; __device__ __forceinline__ void ln_rows(const Params& p, const int row0, const int lane, const f32x4 (&gv)[4], const f32x4 (&bv)[4]) {
;     ...
;   float s[NRW], s2[NRW];
; #pragma unroll
;   for (int h = 0; h < NRW; ++h) { s[h] = 0.f;
; #pragma unroll
;     for (int j = 0; j < 4; ++j) s[h] += (v[h][j].x + v[h][j].y) + (v[h][j].z + v[h][j].w); }
; #pragma unroll
;   for (int o = 1; o < 64; o <<= 1) {
; #pragma unroll
;     for (int h = 0; h < NRW; ++h) s[h] += __shfl_xor(s[h], o);
;   }
; #pragma unroll
;   for (int h = 0; h < NRW; ++h) { const float mean = s[h] * (1.f / DM); s2[h] = 0.f;
; #pragma unroll
;     for (int j = 0; j < 4; ++j) { v[h][j] = v[h][j] - mean; s2[h] += (v[h][j].x * v[h][j].x + v[h][j].y * v[h][j].y) + (v[h][j].z * v[h][j].z + v[h][j].w * v[h][j].w); } }
; #pragma unroll
;   for (int o = 1; o < 64; o <<= 1) {
; #pragma unroll
;     for (int h = 0; h < NRW; ++h) s2[h] += __shfl_xor(s2[h], o);
;   }
	v_add_f32_e32 v39, v39, v46
	v_pk_add_f32 v[90:91], v[92:93], v[98:99]
	ds_bpermute_b32 v46, v78, v39
	v_add_f32_e32 v44, v90, v91
	ds_bpermute_b32 v48, v41, v44
	s_waitcnt lgkmcnt(1)
	v_add_f32_e32 v39, v39, v46
	ds_bpermute_b32 v46, v79, v39
	s_waitcnt lgkmcnt(1)
	v_add_f32_e32 v44, v44, v48
	ds_bpermute_b32 v48, v78, v44
	s_waitcnt lgkmcnt(1)
	v_add_f32_e32 v39, v39, v46
	ds_bpermute_b32 v46, v80, v39
	s_waitcnt lgkmcnt(1)
	v_add_f32_e32 v44, v44, v48
	ds_bpermute_b32 v48, v79, v44
	s_waitcnt lgkmcnt(1)
	v_add_f32_e32 v39, v39, v46
	ds_bpermute_b32 v46, v81, v39
	s_waitcnt lgkmcnt(1)
	v_add_f32_e32 v44, v44, v48
	ds_bpermute_b32 v48, v80, v44
	s_waitcnt lgkmcnt(1)
	v_add_f32_e32 v39, v39, v46
	ds_bpermute_b32 v46, v82, v39
	s_waitcnt lgkmcnt(1)
	v_add_f32_e32 v44, v44, v48
	ds_bpermute_b32 v48, v81, v44
	s_waitcnt lgkmcnt(1)
	v_add_f32_e32 v39, v39, v46
	v_fmac_f32_e32 v86, 0xba800000, v39
	s_waitcnt lgkmcnt(0)
	v_add_f32_e32 v44, v44, v48
	ds_bpermute_b32 v48, v82, v44
	v_fmac_f32_e32 v87, 0xba800000, v39
	v_fmac_f32_e32 v77, 0xba800000, v39
	v_fmac_f32_e32 v88, 0xba800000, v39
	v_fmac_f32_e32 v89, 0xba800000, v39
	v_fmac_f32_e32 v75, 0xba800000, v39
	v_fmac_f32_e32 v76, 0xba800000, v39
	v_fmac_f32_e32 v74, 0xba800000, v39
	v_mov_b32_e32 v90, v77
	v_mov_b32_e32 v91, v87
	v_mov_b32_e32 v77, v86
	v_mov_b32_e32 v86, v75
	v_mov_b32_e32 v87, v89
	v_mov_b32_e32 v75, v88
	v_pk_mul_f32 v[88:89], v[90:91], v[90:91]
	v_pk_mul_f32 v[92:93], v[76:77], v[76:77]
	v_pk_mul_f32 v[96:97], v[86:87], v[86:87]
	v_pk_mul_f32 v[98:99], v[74:75], v[74:75]
	v_fmac_f32_e32 v66, 0xba800000, v39
	v_fmac_f32_e32 v68, 0xba800000, v39
	v_pk_mov_b32 v[104:105], v[92:93], v[88:89] op_sel:[1,0]
	v_mov_b32_e32 v93, v89
	v_pk_mov_b32 v[88:89], v[98:99], v[96:97] op_sel:[1,0]
	v_mov_b32_e32 v99, v97
	s_waitcnt lgkmcnt(0)
	v_add_f32_e32 v48, v44, v48
	v_fmac_f32_e32 v67, 0xba800000, v39
	v_fmac_f32_e32 v69, 0xba800000, v39
	v_mul_f32_e32 v44, v66, v66
	v_mul_f32_e32 v46, v68, v68
	v_pk_add_f32 v[92:93], v[104:105], v[92:93]
	v_pk_add_f32 v[88:89], v[88:89], v[98:99]
	v_fmac_f32_e32 v57, 0xba800000, v39
	v_fmac_f32_e32 v61, 0xba800000, v39
	v_fmac_f32_e32 v59, 0xba800000, v39
	v_pk_fma_f32 v[100:101], v[66:67], v[66:67], v[44:45] op_sel_hi:[1,1,0]
	v_pk_fma_f32 v[102:103], v[68:69], v[68:69], v[46:47] op_sel_hi:[1,1,0]
	v_pk_add_f32 v[92:93], v[92:93], v[92:93] op_sel_hi:[0,1]
	v_pk_add_f32 v[88:89], v[88:89], v[88:89] op_sel_hi:[0,1]
	v_fmac_f32_e32 v63, 0xba800000, v39
	v_mul_f32_e32 v100, v63, v63
	v_mul_f32_e32 v102, v59, v59
	v_mul_f32_e32 v92, v61, v61
	v_mul_f32_e32 v88, v57, v57
	v_fmac_f32_e32 v94, 0xba800000, v48
	v_fmac_f32_e32 v95, 0xba800000, v48
	v_fmac_f32_e32 v71, 0xba800000, v48
	v_pk_add_f32 v[96:97], v[100:101], v[102:103]
	v_pk_add_f32 v[88:89], v[92:93], v[88:89]
	v_fmac_f32_e32 v70, 0xba800000, v48
	v_mov_b32_e32 v92, v71
	v_mov_b32_e32 v93, v95
	v_mov_b32_e32 v71, v94
	v_pk_add_f32 v[88:89], v[96:97], v[88:89]
	v_pk_mul_f32 v[96:97], v[92:93], v[92:93]
	v_pk_mul_f32 v[94:95], v[70:71], v[70:71]
	v_fmac_f32_e32 v84, 0xba800000, v48
	v_fmac_f32_e32 v85, 0xba800000, v48
	v_fmac_f32_e32 v73, 0xba800000, v48
	v_pk_mov_b32 v[98:99], v[94:95], v[96:97] op_sel:[1,0]
	v_mov_b32_e32 v95, v97
	v_fmac_f32_e32 v72, 0xba800000, v48
	v_mov_b32_e32 v96, v73
	v_mov_b32_e32 v97, v85
	v_mov_b32_e32 v73, v84
	v_pk_add_f32 v[94:95], v[98:99], v[94:95]
	v_pk_mul_f32 v[98:99], v[96:97], v[96:97]
	v_pk_mul_f32 v[84:85], v[72:73], v[72:73]
	v_fmac_f32_e32 v52, 0xba800000, v48
	v_pk_mov_b32 v[100:101], v[84:85], v[98:99] op_sel:[1,0]
	v_mov_b32_e32 v85, v99
	v_fmac_f32_e32 v53, 0xba800000, v48
	v_fmac_f32_e32 v54, 0xba800000, v48
	v_mul_f32_e32 v44, v52, v52
	v_pk_add_f32 v[84:85], v[100:101], v[84:85]
	v_fmac_f32_e32 v55, 0xba800000, v48
	v_pk_fma_f32 v[98:99], v[52:53], v[52:53], v[44:45] op_sel_hi:[1,1,0]
	v_mul_f32_e32 v44, v54, v54
	v_pk_add_f32 v[94:95], v[94:95], v[94:95] op_sel_hi:[0,1]
	v_pk_add_f32 v[84:85], v[84:85], v[84:85] op_sel_hi:[0,1]
	v_pk_fma_f32 v[100:101], v[54:55], v[54:55], v[44:45] op_sel_hi:[1,1,0]
	v_fmac_f32_e32 v45, 0xba800000, v48
	v_fmac_f32_e32 v49, 0xba800000, v48
	v_fmac_f32_e32 v47, 0xba800000, v48
	v_fmac_f32_e32 v51, 0xba800000, v48
	v_mul_f32_e32 v98, v51, v51
	v_mul_f32_e32 v100, v47, v47
	v_mul_f32_e32 v94, v49, v49
	v_mul_f32_e32 v84, v45, v45
	v_pk_add_f32 v[98:99], v[98:99], v[100:101]
	v_pk_add_f32 v[84:85], v[94:95], v[84:85]
	v_mov_b32_e32 v95, v88
	v_pk_add_f32 v[84:85], v[98:99], v[84:85]
	v_mov_b32_e32 v58, v63
	v_mov_b32_e32 v94, v84
	v_mov_b32_e32 v88, v85
	v_pk_add_f32 v[84:85], v[94:95], v[88:89]
	ds_bpermute_b32 v89, v41, v85
	ds_bpermute_b32 v88, v41, v84
	v_mov_b32_e32 v56, v61
	v_mov_b32_e32 v46, v51
	s_waitcnt lgkmcnt(0)
; __device__ __forceinline__ u32x2 pk4(f32x4 v) { u32x2 r; r.x = pk2(v.x, v.y); r.y = pk2(v.z, v.w); return r; }
; template <int WHICH, int NRW>
; __device__ __forceinline__ void ln_rows(const Params& p, const int row0, const int lane, const f32x4 (&gv)[4], const f32x4 (&bv)[4]) {
;     ...
; #pragma unroll
;   for (int h = 0; h < NRW; ++h) {
;     const int row = row0 + h;
;     const float rstd = rsqrtf(s2[h] * (1.f / DM) + LN_EPS_F);
; #pragma unroll
;     for (int j = 0; j < 4; ++j) {
;       const f32x4 o = v[h][j] * rstd * gv[j] + bv[j];
;       if (WHICH == 1) *(u32x2*)(X1b + (size_t)row * DM + j * 256 + lane * 4) = pk4(o);
;       else *(f32x4*)(p.out + (size_t)row * DM + j * 256 + lane * 4) = o;
;     }
;   }
	v_pk_add_f32 v[84:85], v[84:85], v[88:89]
	ds_bpermute_b32 v89, v78, v85
	ds_bpermute_b32 v88, v78, v84
	s_waitcnt lgkmcnt(0)
	v_pk_add_f32 v[84:85], v[84:85], v[88:89]
	ds_bpermute_b32 v89, v79, v85
	ds_bpermute_b32 v88, v79, v84
	s_waitcnt lgkmcnt(0)
	v_pk_add_f32 v[84:85], v[84:85], v[88:89]
	ds_bpermute_b32 v89, v80, v85
	ds_bpermute_b32 v88, v80, v84
	s_waitcnt lgkmcnt(0)
	v_pk_add_f32 v[84:85], v[84:85], v[88:89]
	ds_bpermute_b32 v89, v81, v85
	ds_bpermute_b32 v88, v81, v84
	s_waitcnt lgkmcnt(0)
	v_pk_add_f32 v[84:85], v[84:85], v[88:89]
	ds_bpermute_b32 v89, v82, v85
	ds_bpermute_b32 v88, v82, v84
	s_waitcnt lgkmcnt(0)
	v_pk_add_f32 v[84:85], v[84:85], v[88:89]
	s_nop 0
	v_pk_fma_f32 v[84:85], v[84:85], s[8:9], v[40:41] op_sel_hi:[1,0,0]
	s_nop 0
	v_mul_f32_e32 v39, 0x4b800000, v85
	v_cmp_gt_f32_e32 vcc, s9, v85
	s_nop 1
	v_cndmask_b32_e32 v39, v85, v39, vcc
	v_rsq_f32_e32 v39, v39
	s_nop 0
	v_mul_f32_e32 v44, 0x45800000, v39
	v_cndmask_b32_e32 v44, v39, v44, vcc
	v_mul_f32_e32 v39, 0x4b800000, v84
	v_cmp_gt_f32_e32 vcc, s9, v84
	v_pk_mul_f32 v[76:77], v[76:77], v[44:45] op_sel_hi:[1,0]
	v_pk_mul_f32 v[88:89], v[90:91], v[44:45] op_sel_hi:[1,0]
	v_cndmask_b32_e32 v39, v84, v39, vcc
	v_rsq_f32_e32 v39, v39
	v_pk_fma_f32 v[88:89], v[4:5], v[88:89], v[8:9]
	v_pk_fma_f32 v[76:77], v[2:3], v[76:77], v[6:7]
	v_pk_mul_f32 v[58:59], v[58:59], v[44:45] op_sel_hi:[1,0]
	v_cvt_pk_bf16_f32 v76, v76, v77
	v_cvt_pk_bf16_f32 v77, v88, v89
	v_pk_mul_f32 v[56:57], v[56:57], v[44:45] op_sel_hi:[1,0]
	global_store_dwordx2 v[64:65], v[76:77], off
	v_pk_mul_f32 v[74:75], v[74:75], v[44:45] op_sel_hi:[1,0]
	v_pk_mul_f32 v[76:77], v[86:87], v[44:45] op_sel_hi:[1,0]
	v_pk_mul_f32 v[66:67], v[66:67], v[44:45] op_sel_hi:[1,0]
	v_pk_mul_f32 v[68:69], v[68:69], v[44:45] op_sel_hi:[1,0]
	v_pk_fma_f32 v[56:57], v[28:29], v[56:57], v[32:33]
	v_pk_fma_f32 v[58:59], v[26:27], v[58:59], v[30:31]
	v_mul_f32_e32 v44, 0x45800000, v39
	v_cvt_pk_bf16_f32 v58, v58, v59
	v_cvt_pk_bf16_f32 v59, v56, v57
	v_cndmask_b32_e32 v48, v39, v44, vcc
	global_store_dwordx2 v[64:65], v[58:59], off offset:1536
	v_pk_mul_f32 v[56:57], v[70:71], v[48:49] op_sel_hi:[1,0]
	v_pk_mul_f32 v[58:59], v[92:93], v[48:49] op_sel_hi:[1,0]
	v_pk_fma_f32 v[56:57], v[2:3], v[56:57], v[6:7]
	v_pk_fma_f32 v[58:59], v[4:5], v[58:59], v[8:9]
	v_cvt_pk_bf16_f32 v56, v56, v57
	v_cvt_pk_bf16_f32 v57, v58, v59
	v_mov_b32_e32 v44, v49
	global_store_dwordx2 v[42:43], v[56:57], off
	v_pk_mul_f32 v[56:57], v[72:73], v[48:49] op_sel_hi:[1,0]
	v_pk_mul_f32 v[58:59], v[96:97], v[48:49] op_sel_hi:[1,0]
	v_pk_mul_f32 v[52:53], v[52:53], v[48:49] op_sel_hi:[1,0]
	v_pk_mul_f32 v[54:55], v[54:55], v[48:49] op_sel_hi:[1,0]
	v_pk_mul_f32 v[46:47], v[46:47], v[48:49] op_sel_hi:[1,0]
	v_pk_mul_f32 v[44:45], v[44:45], v[48:49] op_sel_hi:[1,0]
	v_pk_fma_f32 v[76:77], v[12:13], v[76:77], v[16:17]
	v_pk_fma_f32 v[74:75], v[10:11], v[74:75], v[14:15]
	v_pk_fma_f32 v[68:69], v[20:21], v[68:69], v[24:25]
	v_pk_fma_f32 v[66:67], v[18:19], v[66:67], v[22:23]
	v_pk_fma_f32 v[58:59], v[12:13], v[58:59], v[16:17]
	v_pk_fma_f32 v[56:57], v[10:11], v[56:57], v[14:15]
	v_pk_fma_f32 v[54:55], v[20:21], v[54:55], v[24:25]
	v_pk_fma_f32 v[52:53], v[18:19], v[52:53], v[22:23]
	v_pk_fma_f32 v[44:45], v[28:29], v[44:45], v[32:33]
	v_pk_fma_f32 v[46:47], v[26:27], v[46:47], v[30:31]
	v_cmp_lt_i32_e32 vcc, s10, v83
	v_cvt_pk_bf16_f32 v74, v74, v75
	v_cvt_pk_bf16_f32 v75, v76, v77
	v_cvt_pk_bf16_f32 v66, v66, v67
	v_cvt_pk_bf16_f32 v67, v68, v69
	v_cvt_pk_bf16_f32 v56, v56, v57
	v_cvt_pk_bf16_f32 v57, v58, v59
	v_cvt_pk_bf16_f32 v52, v52, v53
	v_cvt_pk_bf16_f32 v53, v54, v55
	v_cvt_pk_bf16_f32 v46, v46, v47
	v_cvt_pk_bf16_f32 v47, v44, v45
	s_or_b64 s[6:7], vcc, s[6:7]
	global_store_dwordx2 v[64:65], v[74:75], off offset:512
	global_store_dwordx2 v[64:65], v[66:67], off offset:1024
	global_store_dwordx2 v[42:43], v[56:57], off offset:512
	global_store_dwordx2 v[42:43], v[52:53], off offset:1024
	global_store_dwordx2 v[42:43], v[46:47], off offset:1536
	s_andn2_b64 exec, exec, s[6:7]
	s_cbranch_execnz .LBB0_891

; __device__ __forceinline__ f32x4 unpk4(u32x2 w) { f32x4 r; r.x = bflo(w.x); r.y = bfhi(w.x); r.z = bflo(w.y); r.w = bfhi(w.y); return r; }
; template <int WHICH, int NRW>
; __device__ __forceinline__ void ln_rows(const Params& p, const int row0, const int lane, const f32x4 (&gv)[4], const f32x4 (&bv)[4]) {
;   bf16_t* X1b = (bf16_t*)(p.ws + OFF_X1B);
;   f32x4 v[NRW][4];
; #pragma unroll
;   for (int h = 0; h < NRW; ++h) {
;     const int row = row0 + h;
;     if (row < MP) {
;       const bf16_t* xr = (const bf16_t*)(p.ws + (WHICH == 1 ? OFF_PRE1 : OFF_PRE2)) + (size_t)row * DM;
; #pragma unroll
;       for (int j = 0; j < 4; ++j) v[h][j] = unpk4(*(const u32x2*)(xr + j * 256 + lane * 4));
;     } else {
;       const float* SL = (const float*)(p.ws + (WHICH == 1 ? OFF_SLAB_WO : OFF_SLAB_DN)) + (size_t)(row - MP) * DM;
;       constexpr int NS = (WHICH == 1) ? 8 : 11;
; #pragma unroll
;       for (int j = 0; j < 4; ++j) {
;         f32x4 a;
;         if (WHICH == 1) a = *(const f32x4*)(p.in[1] + (size_t)(row - MP) * DM + j * 256 + lane * 4) * ALPHA_F;
;         else a = unpk4(*(const u32x2*)(X1b + (size_t)row * DM + j * 256 + lane * 4)) * ALPHA_F;
; #pragma unroll
;         for (int q = 0; q < NS; ++q) a += *(const f32x4*)(SL + (size_t)q * MS * DM + j * 256 + lane * 4);
;         v[h][j] = a;
;       }
;     }
;   }
;   float s[NRW], s2[NRW];
; #pragma unroll
;   for (int h = 0; h < NRW; ++h) { s[h] = 0.f;
; #pragma unroll
;     for (int j = 0; j < 4; ++j) s[h] += (v[h][j].x + v[h][j].y) + (v[h][j].z + v[h][j].w); }
; template <int WHICH>
; __device__ __forceinline__ void ln_phase(const Params& p) {
;   const int lane = threadIdx.x & 63, wid = threadIdx.x >> 6;
;   const int gw = blockIdx.x * NWAVE + wid, NGW = gridDim.x * NWAVE;
;   const float* gam = p.in[WHICH == 1 ? 20 : 26]; const float* bet = p.in[WHICH == 1 ? 21 : 27];
;   f32x4 gv[4], bv[4];
; #pragma unroll
;   for (int j = 0; j < 4; ++j) { gv[j] = *(const f32x4*)(gam + j * 256 + lane * 4); bv[j] = *(const f32x4*)(bet + j * 256 + lane * 4); }
;   for (int rp = gw; rp < MP / 2; rp += NGW) ln_rows<WHICH, 2>(p, rp * 2, lane, gv, bv);
;   for (int row = MP + gw; row < MT; row += NGW) ln_rows<WHICH, 1>(p, row, lane, gv, bv);
.LBB0_1310:
	s_or_b64 exec, exec, s[2:3]
	v_readlane_b32 s8, v244, 4
	v_readlane_b32 s9, v244, 5
	v_readlane_b32 s10, v244, 6
	v_readlane_b32 s11, v244, 7
	v_readlane_b32 s12, v244, 8
	v_readlane_b32 s13, v244, 9
	v_readlane_b32 s14, v244, 10
	v_readlane_b32 s15, v244, 11
	s_mov_b64 s[8:9], s[12:13]
	s_waitcnt lgkmcnt(0)
	s_barrier
	s_mov_b64 s[10:11], s[14:15]
	global_load_dwordx4 v[0:3], v188, s[8:9]
	global_load_dwordx4 v[4:7], v188, s[10:11]
	global_load_dwordx4 v[8:11], v188, s[8:9] offset:1024
	global_load_dwordx4 v[12:15], v188, s[10:11] offset:1024
	global_load_dwordx4 v[16:19], v188, s[8:9] offset:2048
	global_load_dwordx4 v[20:23], v188, s[10:11] offset:2048
	global_load_dwordx4 v[24:27], v188, s[8:9] offset:3072
	global_load_dwordx4 v[28:31], v188, s[10:11] offset:3072
	s_and_saveexec_b64 s[2:3], s[4:5]
	s_cbranch_execz .LBB0_1313
	v_mbcnt_hi_u32_b32 v32, -1, v185
	v_and_b32_e32 v33, 64, v32
	v_add_u32_e32 v33, 64, v33
	v_xor_b32_e32 v34, 1, v32
	v_cmp_lt_i32_e32 vcc, v34, v33
	v_mov_b32_e32 v191, 0
	v_readlane_b32 s4, v244, 0
	v_cndmask_b32_e32 v34, v32, v34, vcc
	v_lshlrev_b32_e32 v37, 2, v34
	v_xor_b32_e32 v34, 2, v32
	v_cmp_lt_i32_e32 vcc, v34, v33
	v_mov_b32_e32 v189, v191
	v_readlane_b32 s5, v244, 1
	v_cndmask_b32_e32 v34, v32, v34, vcc
	v_lshlrev_b32_e32 v72, 2, v34
	v_xor_b32_e32 v34, 4, v32
	v_cmp_lt_i32_e32 vcc, v34, v33
	v_readlane_b32 s6, v244, 2
	v_readlane_b32 s7, v244, 3
	v_cndmask_b32_e32 v34, v32, v34, vcc
	v_lshlrev_b32_e32 v73, 2, v34
	v_xor_b32_e32 v34, 8, v32
	v_cmp_lt_i32_e32 vcc, v34, v33
	s_lshl_b32 s7, s33, 4
	s_mov_b32 s6, 0x3a800000
	v_cndmask_b32_e32 v34, v32, v34, vcc
	v_lshlrev_b32_e32 v74, 2, v34
	v_xor_b32_e32 v34, 16, v32
	v_cmp_lt_i32_e32 vcc, v34, v33
	v_mov_b32_e32 v36, 0x3727c5ac
	s_mov_b32 s8, 0x800000
	v_cndmask_b32_e32 v34, v32, v34, vcc
	v_lshlrev_b32_e32 v75, 2, v34
	v_xor_b32_e32 v34, 32, v32
	v_cmp_lt_i32_e32 vcc, v34, v33
	s_movk_i32 s9, 0x1fff
	v_mov_b32_e32 v77, v182
	v_cndmask_b32_e32 v32, v32, v34, vcc
	v_lshlrev_b32_e32 v76, 2, v32
	v_lshl_add_u64 v[32:33], s[22:23], 0, v[190:191]
	v_lshl_add_u64 v[34:35], s[4:5], 0, v[188:189]
	s_mov_b64 s[4:5], 0
	s_cmp_lg_u32 s33, 0x100
	s_cbranch_scc1 .Lln2map_keep
	v_readlane_b32 s98, v244, 33
	s_nop 3
	s_and_b32 s99, s98, 7
	s_lshl_b32 s99, s99, 11
	s_lshr_b32 s98, s98, 3
	s_lshl_b32 s98, s98, 6
	s_add_u32 s98, s98, s99
	v_and_b32_e32 v192, 7, v182
	v_lshl_add_u32 v192, v192, 1, s98
	s_mov_b32 s7, 16
.Lln2map_keep:
.LBB0_1312:
	v_ashrrev_i32_e32 v193, 31, v192
	v_lshlrev_b64 v[38:39], 11, v[192:193]
	v_lshl_add_u64 v[38:39], v[32:33], 0, v[38:39]
	global_load_dwordx2 v[40:41], v[38:39], off offset:1024
	global_load_dwordx2 v[42:43], v[38:39], off offset:1536
	global_load_dwordx2 v[44:45], v[38:39], off
	global_load_dwordx2 v[46:47], v[38:39], off offset:512
	v_add_u32_e32 v38, 1, v192
	v_ashrrev_i32_e32 v39, 31, v38
	v_lshlrev_b64 v[48:49], 11, v[38:39]
	v_lshl_add_u64 v[48:49], v[32:33], 0, v[48:49]
	global_load_dwordx2 v[50:51], v[48:49], off offset:1024
	global_load_dwordx2 v[64:65], v[48:49], off offset:1536
	global_load_dwordx2 v[66:67], v[48:49], off
	global_load_dwordx2 v[78:79], v[48:49], off offset:512
	v_lshlrev_b64 v[38:39], 12, v[38:39]
	v_add_u32_e32 v77, s66, v77
	s_waitcnt vmcnt(7)
	v_lshlrev_b32_e32 v60, 16, v40
	v_and_b32_e32 v61, 0xffff0000, v40
	s_waitcnt vmcnt(5)
	v_lshlrev_b32_e32 v69, 16, v45
	v_lshlrev_b32_e32 v68, 16, v44
	v_and_b32_e32 v81, 0xffff0000, v45
	v_and_b32_e32 v80, 0xffff0000, v44
	s_waitcnt vmcnt(4)
	v_lshlrev_b32_e32 v71, 16, v47
	v_lshlrev_b32_e32 v70, 16, v46
	v_and_b32_e32 v83, 0xffff0000, v47
	v_and_b32_e32 v82, 0xffff0000, v46
	v_pk_add_f32 v[84:85], v[68:69], v[80:81]
	v_pk_add_f32 v[86:87], v[70:71], v[82:83]
	v_lshlrev_b32_e32 v62, 16, v41
	v_and_b32_e32 v63, 0xffff0000, v41
	v_lshlrev_b32_e32 v59, 16, v42
	v_and_b32_e32 v55, 0xffff0000, v42
	v_add_f32_e32 v42, v84, v85
	v_pk_add_f32 v[84:85], v[86:87], v[86:87] op_sel:[0,1] op_sel_hi:[1,0]
	v_lshlrev_b32_e32 v57, 16, v43
	v_and_b32_e32 v53, 0xffff0000, v43
	v_add_f32_e32 v56, v60, v61
	v_add_f32_e32 v52, v62, v63
	v_add_f32_e32 v58, 0, v42
	v_mov_b32_e32 v85, v55
	s_waitcnt vmcnt(3)
	v_lshlrev_b32_e32 v48, 16, v50
	v_and_b32_e32 v49, 0xffff0000, v50
	v_lshlrev_b32_e32 v50, 16, v51
	v_and_b32_e32 v51, 0xffff0000, v51
	s_waitcnt vmcnt(2)
	v_lshlrev_b32_e32 v47, 16, v64
	v_and_b32_e32 v43, 0xffff0000, v64
	v_lshlrev_b32_e32 v45, 16, v65
	v_and_b32_e32 v41, 0xffff0000, v65
	s_waitcnt vmcnt(1)
	v_lshlrev_b32_e32 v65, 16, v67
	v_lshlrev_b32_e32 v64, 16, v66
	v_and_b32_e32 v89, 0xffff0000, v67
	v_and_b32_e32 v88, 0xffff0000, v66
	s_waitcnt vmcnt(0)
	v_lshlrev_b32_e32 v67, 16, v79
	v_lshlrev_b32_e32 v66, 16, v78
	v_and_b32_e32 v79, 0xffff0000, v79
	v_and_b32_e32 v78, 0xffff0000, v78
	v_pk_add_f32 v[86:87], v[56:57], v[52:53]
	v_pk_add_f32 v[84:85], v[58:59], v[84:85]
	v_pk_add_f32 v[90:91], v[64:65], v[88:89]
	v_pk_add_f32 v[92:93], v[66:67], v[78:79]
	v_add_f32_e32 v44, v48, v49
	v_add_f32_e32 v40, v50, v51
	v_pk_add_f32 v[84:85], v[84:85], v[86:87]
	v_add_f32_e32 v42, v90, v91
	v_pk_add_f32 v[90:91], v[92:93], v[92:93] op_sel:[0,1] op_sel_hi:[1,0]
	v_pk_add_f32 v[92:93], v[44:45], v[40:41]
	v_add_f32_e32 v40, v84, v85
	ds_bpermute_b32 v44, v37, v40
	v_add_f32_e32 v46, 0, v42
	v_mov_b32_e32 v91, v43
	v_pk_add_f32 v[86:87], v[46:47], v[90:91]
	s_waitcnt lgkmcnt(0)
	v_add_f32_e32 v40, v40, v44
	v_pk_add_f32 v[84:85], v[86:87], v[92:93]
	ds_bpermute_b32 v44, v72, v40
	v_add_f32_e32 v42, v84, v85
	ds_bpermute_b32 v46, v37, v42
	s_waitcnt lgkmcnt(1)
	v_add_f32_e32 v40, v40, v44
	ds_bpermute_b32 v44, v73, v40
	s_waitcnt lgkmcnt(1)
; template <int WHICH, int NRW>
; __device__ __forceinline__ void ln_rows(const Params& p, const int row0, const int lane, const f32x4 (&gv)[4], const f32x4 (&bv)[4]) {
;     ...
; #pragma unroll
;   for (int o = 1; o < 64; o <<= 1) {
; #pragma unroll
;     for (int h = 0; h < NRW; ++h) s[h] += __shfl_xor(s[h], o);
;   }
; #pragma unroll
;   for (int h = 0; h < NRW; ++h) { const float mean = s[h] * (1.f / DM); s2[h] = 0.f;
; #pragma unroll
;     for (int j = 0; j < 4; ++j) { v[h][j] = v[h][j] - mean; s2[h] += (v[h][j].x * v[h][j].x + v[h][j].y * v[h][j].y) + (v[h][j].z * v[h][j].z + v[h][j].w * v[h][j].w); } }
; #pragma unroll
;   for (int o = 1; o < 64; o <<= 1) {
; #pragma unroll
;     for (int h = 0; h < NRW; ++h) s2[h] += __shfl_xor(s2[h], o);
;   }
	v_add_f32_e32 v42, v42, v46
	ds_bpermute_b32 v46, v72, v42
	s_waitcnt lgkmcnt(1)
	v_add_f32_e32 v40, v40, v44
	ds_bpermute_b32 v44, v74, v40
	s_waitcnt lgkmcnt(1)
	v_add_f32_e32 v42, v42, v46
	ds_bpermute_b32 v46, v73, v42
	s_waitcnt lgkmcnt(1)
	v_add_f32_e32 v40, v40, v44
	ds_bpermute_b32 v44, v75, v40
	s_waitcnt lgkmcnt(1)
	v_add_f32_e32 v42, v42, v46
	ds_bpermute_b32 v46, v74, v42
	s_waitcnt lgkmcnt(1)
	v_add_f32_e32 v40, v40, v44
	ds_bpermute_b32 v44, v76, v40
	s_waitcnt lgkmcnt(1)
	v_add_f32_e32 v42, v42, v46
	ds_bpermute_b32 v46, v75, v42
	s_waitcnt lgkmcnt(1)
	v_add_f32_e32 v44, v40, v44
	v_fmac_f32_e32 v80, 0xba800000, v44
	s_waitcnt lgkmcnt(0)
	v_add_f32_e32 v42, v42, v46
	ds_bpermute_b32 v46, v76, v42
	v_fmac_f32_e32 v81, 0xba800000, v44
	v_fmac_f32_e32 v69, 0xba800000, v44
	v_fmac_f32_e32 v82, 0xba800000, v44
	v_fmac_f32_e32 v83, 0xba800000, v44
	v_fmac_f32_e32 v71, 0xba800000, v44
	v_fmac_f32_e32 v68, 0xba800000, v44
	v_fmac_f32_e32 v70, 0xba800000, v44
	v_mov_b32_e32 v84, v69
	v_mov_b32_e32 v85, v81
	v_mov_b32_e32 v69, v80
	v_mov_b32_e32 v86, v71
	v_mov_b32_e32 v87, v83
	v_mov_b32_e32 v71, v82
	v_pk_mul_f32 v[80:81], v[84:85], v[84:85]
	v_pk_mul_f32 v[82:83], v[68:69], v[68:69]
	v_pk_mul_f32 v[90:91], v[86:87], v[86:87]
	v_pk_mul_f32 v[92:93], v[70:71], v[70:71]
	v_fmac_f32_e32 v60, 0xba800000, v44
	v_fmac_f32_e32 v62, 0xba800000, v44
	v_pk_mov_b32 v[98:99], v[82:83], v[80:81] op_sel:[1,0]
	v_mov_b32_e32 v83, v81
	v_pk_mov_b32 v[80:81], v[92:93], v[90:91] op_sel:[1,0]
	v_mov_b32_e32 v93, v91
	s_waitcnt lgkmcnt(0)
	v_add_f32_e32 v46, v42, v46
	v_fmac_f32_e32 v61, 0xba800000, v44
	v_fmac_f32_e32 v63, 0xba800000, v44
	v_mul_f32_e32 v40, v60, v60
	v_mul_f32_e32 v42, v62, v62
	v_pk_add_f32 v[82:83], v[98:99], v[82:83]
	v_pk_add_f32 v[80:81], v[80:81], v[92:93]
	v_fmac_f32_e32 v53, 0xba800000, v44
	v_fmac_f32_e32 v57, 0xba800000, v44
	v_fmac_f32_e32 v55, 0xba800000, v44
	v_pk_fma_f32 v[94:95], v[60:61], v[60:61], v[40:41] op_sel_hi:[1,1,0]
	v_pk_fma_f32 v[96:97], v[62:63], v[62:63], v[42:43] op_sel_hi:[1,1,0]
	v_pk_add_f32 v[82:83], v[82:83], v[82:83] op_sel_hi:[0,1]
	v_pk_add_f32 v[80:81], v[80:81], v[80:81] op_sel_hi:[0,1]
	v_fmac_f32_e32 v59, 0xba800000, v44
	v_mul_f32_e32 v94, v59, v59
	v_mul_f32_e32 v96, v55, v55
	v_mul_f32_e32 v82, v57, v57
	v_mul_f32_e32 v80, v53, v53
	v_fmac_f32_e32 v88, 0xba800000, v46
	v_fmac_f32_e32 v89, 0xba800000, v46
	v_fmac_f32_e32 v65, 0xba800000, v46
	v_pk_add_f32 v[90:91], v[94:95], v[96:97]
	v_pk_add_f32 v[80:81], v[82:83], v[80:81]
	v_fmac_f32_e32 v64, 0xba800000, v46
	v_mov_b32_e32 v82, v65
	v_mov_b32_e32 v83, v89
	v_mov_b32_e32 v65, v88
	v_pk_add_f32 v[80:81], v[90:91], v[80:81]
	v_pk_mul_f32 v[90:91], v[82:83], v[82:83]
	v_pk_mul_f32 v[88:89], v[64:65], v[64:65]
	v_fmac_f32_e32 v78, 0xba800000, v46
	v_fmac_f32_e32 v79, 0xba800000, v46
	v_fmac_f32_e32 v67, 0xba800000, v46
	v_pk_mov_b32 v[92:93], v[88:89], v[90:91] op_sel:[1,0]
	v_mov_b32_e32 v89, v91
	v_fmac_f32_e32 v66, 0xba800000, v46
	v_mov_b32_e32 v90, v67
	v_mov_b32_e32 v91, v79
	v_mov_b32_e32 v67, v78
	v_pk_add_f32 v[88:89], v[92:93], v[88:89]
	v_pk_mul_f32 v[92:93], v[90:91], v[90:91]
	v_pk_mul_f32 v[78:79], v[66:67], v[66:67]
	v_fmac_f32_e32 v48, 0xba800000, v46
	v_pk_mov_b32 v[94:95], v[78:79], v[92:93] op_sel:[1,0]
	v_mov_b32_e32 v79, v93
	v_fmac_f32_e32 v49, 0xba800000, v46
	v_fmac_f32_e32 v50, 0xba800000, v46
	v_mul_f32_e32 v40, v48, v48
	v_pk_add_f32 v[78:79], v[94:95], v[78:79]
	v_fmac_f32_e32 v51, 0xba800000, v46
	v_pk_fma_f32 v[92:93], v[48:49], v[48:49], v[40:41] op_sel_hi:[1,1,0]
	v_mul_f32_e32 v40, v50, v50
	v_pk_add_f32 v[88:89], v[88:89], v[88:89] op_sel_hi:[0,1]
	v_pk_add_f32 v[78:79], v[78:79], v[78:79] op_sel_hi:[0,1]
	v_pk_fma_f32 v[94:95], v[50:51], v[50:51], v[40:41] op_sel_hi:[1,1,0]
	v_fmac_f32_e32 v41, 0xba800000, v46
	v_fmac_f32_e32 v45, 0xba800000, v46
	v_fmac_f32_e32 v43, 0xba800000, v46
	v_fmac_f32_e32 v47, 0xba800000, v46
	v_mul_f32_e32 v92, v47, v47
	v_mul_f32_e32 v94, v43, v43
	v_mul_f32_e32 v88, v45, v45
	v_mul_f32_e32 v78, v41, v41
	v_pk_add_f32 v[92:93], v[92:93], v[94:95]
	v_pk_add_f32 v[78:79], v[88:89], v[78:79]
	v_mov_b32_e32 v89, v80
	v_pk_add_f32 v[78:79], v[92:93], v[78:79]
	v_mov_b32_e32 v54, v59
	v_mov_b32_e32 v88, v78
	v_mov_b32_e32 v80, v79
	v_pk_add_f32 v[78:79], v[88:89], v[80:81]
	ds_bpermute_b32 v81, v37, v79
	ds_bpermute_b32 v80, v37, v78
	v_mov_b32_e32 v52, v57
	v_lshl_add_u64 v[56:57], v[34:35], 0, v[38:39]
	s_waitcnt lgkmcnt(0)
; __device__ __forceinline__ u32x2 pk4(f32x4 v) { u32x2 r; r.x = pk2(v.x, v.y); r.y = pk2(v.z, v.w); return r; }
; template <int WHICH, int NRW>
; __device__ __forceinline__ void ln_rows(const Params& p, const int row0, const int lane, const f32x4 (&gv)[4], const f32x4 (&bv)[4]) {
;     ...
; #pragma unroll
;   for (int h = 0; h < NRW; ++h) {
;     const int row = row0 + h;
;     const float rstd = rsqrtf(s2[h] * (1.f / DM) + LN_EPS_F);
; #pragma unroll
;     for (int j = 0; j < 4; ++j) {
;       const f32x4 o = v[h][j] * rstd * gv[j] + bv[j];
;       if (WHICH == 1) *(u32x2*)(X1b + (size_t)row * DM + j * 256 + lane * 4) = pk4(o);
;       else *(f32x4*)(p.out + (size_t)row * DM + j * 256 + lane * 4) = o;
;     }
;   }
	v_pk_add_f32 v[78:79], v[78:79], v[80:81]
	ds_bpermute_b32 v81, v72, v79
	ds_bpermute_b32 v80, v72, v78
	s_waitcnt lgkmcnt(0)
	v_pk_add_f32 v[78:79], v[78:79], v[80:81]
	ds_bpermute_b32 v81, v73, v79
	ds_bpermute_b32 v80, v73, v78
	s_waitcnt lgkmcnt(0)
	v_pk_add_f32 v[78:79], v[78:79], v[80:81]
	ds_bpermute_b32 v81, v74, v79
	ds_bpermute_b32 v80, v74, v78
	s_waitcnt lgkmcnt(0)
	v_pk_add_f32 v[78:79], v[78:79], v[80:81]
	ds_bpermute_b32 v81, v75, v79
	ds_bpermute_b32 v80, v75, v78
	s_waitcnt lgkmcnt(0)
	v_pk_add_f32 v[78:79], v[78:79], v[80:81]
	ds_bpermute_b32 v81, v76, v79
	ds_bpermute_b32 v80, v76, v78
	s_waitcnt lgkmcnt(0)
	v_pk_add_f32 v[78:79], v[78:79], v[80:81]
	s_nop 0
	v_pk_fma_f32 v[88:89], v[78:79], s[6:7], v[36:37] op_sel_hi:[1,0,0]
	v_lshlrev_b64 v[78:79], 12, v[192:193]
	v_mul_f32_e32 v40, 0x4b800000, v89
	v_cmp_gt_f32_e32 vcc, s8, v89
	v_lshl_add_u64 v[92:93], v[34:35], 0, v[78:79]
	v_add_u32_e32 v192, s7, v192
	v_cndmask_b32_e32 v40, v89, v40, vcc
	v_rsq_f32_e32 v40, v40
	s_nop 0
	v_mul_f32_e32 v42, 0x45800000, v40
	v_cndmask_b32_e32 v40, v40, v42, vcc
	v_pk_mul_f32 v[68:69], v[68:69], v[40:41] op_sel_hi:[1,0]
	v_pk_mul_f32 v[78:79], v[84:85], v[40:41] op_sel_hi:[1,0]
	v_pk_mul_f32 v[60:61], v[60:61], v[40:41] op_sel_hi:[1,0]
	v_pk_fma_f32 v[80:81], v[2:3], v[78:79], v[6:7]
	v_pk_fma_f32 v[78:79], v[0:1], v[68:69], v[4:5]
	v_pk_mul_f32 v[68:69], v[70:71], v[40:41] op_sel_hi:[1,0]
	v_pk_mul_f32 v[70:71], v[86:87], v[40:41] op_sel_hi:[1,0]
	v_pk_mul_f32 v[62:63], v[62:63], v[40:41] op_sel_hi:[1,0]
	v_pk_mul_f32 v[58:59], v[54:55], v[40:41] op_sel_hi:[1,0]
	v_pk_mul_f32 v[52:53], v[52:53], v[40:41] op_sel_hi:[1,0]
	v_mul_f32_e32 v40, 0x4b800000, v88
	v_cmp_gt_f32_e32 vcc, s8, v88
	v_pk_fma_f32 v[54:55], v[26:27], v[52:53], v[30:31]
	v_pk_fma_f32 v[52:53], v[24:25], v[58:59], v[28:29]
	v_cndmask_b32_e32 v40, v88, v40, vcc
	v_rsq_f32_e32 v40, v40
	global_store_dwordx4 v[92:93], v[52:55], off offset:3072
	v_pk_fma_f32 v[70:71], v[10:11], v[70:71], v[14:15]
	v_pk_fma_f32 v[68:69], v[8:9], v[68:69], v[12:13]
	v_mul_f32_e32 v42, 0x45800000, v40
	v_cndmask_b32_e32 v44, v40, v42, vcc
	v_pk_mul_f32 v[52:53], v[64:65], v[44:45] op_sel_hi:[1,0]
	v_pk_mul_f32 v[54:55], v[82:83], v[44:45] op_sel_hi:[1,0]
	v_pk_fma_f32 v[52:53], v[0:1], v[52:53], v[4:5]
	v_pk_fma_f32 v[54:55], v[2:3], v[54:55], v[6:7]
	global_store_dwordx4 v[56:57], v[52:55], off
	v_pk_mul_f32 v[38:39], v[66:67], v[44:45] op_sel_hi:[1,0]
	v_mov_b32_e32 v42, v47
	v_pk_mul_f32 v[52:53], v[90:91], v[44:45] op_sel_hi:[1,0]
	v_mov_b32_e32 v40, v45
	v_pk_fma_f32 v[54:55], v[10:11], v[52:53], v[14:15]
	v_pk_fma_f32 v[52:53], v[8:9], v[38:39], v[12:13]
	v_pk_mul_f32 v[38:39], v[48:49], v[44:45] op_sel_hi:[1,0]
	v_pk_mul_f32 v[48:49], v[50:51], v[44:45] op_sel_hi:[1,0]
	v_pk_mul_f32 v[40:41], v[40:41], v[44:45] op_sel_hi:[1,0]
	v_pk_fma_f32 v[50:51], v[18:19], v[48:49], v[22:23]
	v_pk_fma_f32 v[48:49], v[16:17], v[38:39], v[20:21]
	v_pk_mul_f32 v[38:39], v[42:43], v[44:45] op_sel_hi:[1,0]
	v_cmp_lt_i32_e32 vcc, s9, v77
	v_pk_fma_f32 v[62:63], v[18:19], v[62:63], v[22:23]
	v_pk_fma_f32 v[60:61], v[16:17], v[60:61], v[20:21]
	v_pk_fma_f32 v[40:41], v[26:27], v[40:41], v[30:31]
	v_pk_fma_f32 v[38:39], v[24:25], v[38:39], v[28:29]
	s_or_b64 s[4:5], vcc, s[4:5]
	global_store_dwordx4 v[92:93], v[78:81], off
	global_store_dwordx4 v[92:93], v[68:71], off offset:1024
	global_store_dwordx4 v[92:93], v[60:63], off offset:2048
	global_store_dwordx4 v[56:57], v[52:55], off offset:1024
	global_store_dwordx4 v[56:57], v[48:51], off offset:2048
	global_store_dwordx4 v[56:57], v[38:41], off offset:3072
	s_andn2_b64 exec, exec, s[4:5]
	s_cbranch_execnz .LBB0_1312
